# RWKV step B from registers: per-lane MFMA A fragments loaded straight from global, B runs in the commit phase, one barrier less per chunk
# baseline (speedup 1.0000x reference)
.LBB0_421:
	s_or_b64 exec, exec, s[18:19]
	s_mul_i32 s52, s36, 0x20800
	s_xor_b64 s[76:77], s[22:23], -1
	s_lshl_b64 s[18:19], s[52:53], 2
	s_add_u32 s18, s20, s18
	v_mov_b32_e32 v6, 0xc200
	v_mov_b32_e32 v7, 0xb000
	s_addc_u32 s19, s21, s19
	v_cndmask_b32_e64 v6, v6, v7, s[16:17]
	s_lshl_b32 s16, s34, 1
	s_add_u32 s20, s20, s16
	s_addc_u32 s21, s21, 0
	s_lshl_b32 s22, s35, 2
	s_add_u32 s18, s18, s22
	s_addc_u32 s19, s19, 0
	s_add_u32 s78, s18, 0x118000
	v_readlane_b32 s18, v255, 3
	v_lshlrev_b32_e32 v4, 1, v116
	s_addc_u32 s79, s19, 0
	v_lshl_add_u32 v61, v235, 2, s18
	s_lshl_b32 s18, s37, 1
	v_and_b32_e32 v5, 14, v4
	v_lshrrev_b32_e32 v7, 2, v116
	s_add_u32 s18, s20, s18
	v_and_b32_e32 v52, 16, v7
	s_addc_u32 s19, s21, 0
	v_lshlrev_b32_e32 v16, 1, v5
	v_ashrrev_i32_e32 v87, 4, v116
	v_add_u32_e32 v64, 0, v4
	v_lshlrev_b32_e32 v67, 5, v5
	v_lshl_add_u64 v[4:5], s[18:19], 0, v[16:17]
	v_lshlrev_b32_e32 v16, 8, v52
	v_lshl_or_b32 v69, v139, 10, v16
	v_lshl_or_b32 v16, v87, 8, v122
	v_add_u32_e32 v92, 16, v87
	v_and_b32_e32 v60, 1, v116
	v_add_u32_e32 v91, 0, v16
	v_lshl_or_b32 v16, v92, 8, v122
	v_add_u32_e32 v93, 0, v16
	v_add_u32_e32 v16, 0x11200, v64
	v_cmp_eq_u32_e32 vcc, 0, v60
	v_or_b32_e32 v7, v52, v140
	v_mul_u32_u24_e32 v7, 0x90, v7
	v_cndmask_b32_e32 v98, v61, v16, vcc
	v_add_u32_e32 v16, 0x11000, v64
	v_cndmask_b32_e32 v99, v61, v16, vcc
	v_add_u32_e32 v16, 0x10e00, v64
	v_cndmask_b32_e32 v100, v61, v16, vcc
	v_add_u32_e32 v16, 0x10c00, v64
	v_cndmask_b32_e32 v101, v61, v16, vcc
	v_add_u32_e32 v16, 0x10a00, v64
	s_mov_b64 s[18:19], 0xe488000
	v_cndmask_b32_e32 v102, v61, v16, vcc
	v_add_u32_e32 v16, 0x10800, v64
	v_add3_u32 v62, 0, v6, v7
	v_or_b32_e32 v6, s38, v140
	v_lshl_add_u64 v[18:19], v[4:5], 0, s[18:19]
	s_mov_b32 s18, 0x5040100
	s_movk_i32 s20, 0xffde
	v_add_u32_e32 v97, v106, v105
	v_cndmask_b32_e32 v103, v61, v16, vcc
	v_add_u32_e32 v16, 0x10600, v64
	v_cmp_eq_u32_e64 s[16:17], 0, v6
	v_perm_b32 v7, v153, v151, s18
	v_perm_b32 v6, v149, v147, s18
	v_perm_b32 v5, v145, v143, s18
	v_perm_b32 v4, v142, v141, s18
	v_perm_b32 v11, v165, v163, s18
	v_perm_b32 v10, v162, v161, s18
	v_perm_b32 v9, v160, v159, s18
	v_perm_b32 v8, v158, v157, s18
	v_perm_b32 v15, v186, v184, s18
	v_perm_b32 v14, v182, v180, s18
	v_perm_b32 v13, v178, v176, s18
	v_perm_b32 v12, v174, v173, s18
	v_perm_b32 v27, v198, v195, s18
	v_perm_b32 v26, v194, v193, s18
	v_perm_b32 v25, v192, v191, s18
	v_perm_b32 v24, v190, v189, s18
	v_perm_b32 v35, v156, v155, s18
	v_perm_b32 v34, v154, v152, s18
	v_perm_b32 v33, v150, v148, s18
	v_perm_b32 v32, v146, v144, s18
	v_perm_b32 v39, v172, v171, s18
	v_perm_b32 v38, v170, v169, s18
	v_perm_b32 v37, v168, v167, s18
	v_perm_b32 v36, v166, v164, s18
	v_perm_b32 v43, v188, v187, s18
	v_perm_b32 v42, v185, v183, s18
	v_perm_b32 v41, v181, v179, s18
	v_perm_b32 v40, v177, v175, s18
	v_perm_b32 v47, v204, v203, s18
	v_perm_b32 v46, v202, v201, s18
	v_perm_b32 v45, v200, v199, s18
	v_perm_b32 v44, v197, v196, s18
	v_mad_u64_u32 v[58:59], s[18:19], v97, s20, v[104:105]
	v_cndmask_b32_e32 v104, v61, v16, vcc
	v_add_u32_e32 v16, 0x10400, v64
	v_cndmask_b32_e32 v105, v61, v16, vcc
	v_add_u32_e32 v16, 0x10200, v64
	v_cndmask_b32_e32 v106, v61, v16, vcc
	v_add_u32_e32 v16, 0x10000, v64
	v_cndmask_b32_e32 v107, v61, v16, vcc
	v_add_u32_e32 v16, 0xfe00, v64
	v_cndmask_b32_e32 v108, v61, v16, vcc
	v_add_u32_e32 v16, 0xfc00, v64
	v_cndmask_b32_e32 v109, v61, v16, vcc
	v_add_u32_e32 v16, 0xfa00, v64
	v_cndmask_b32_e32 v110, v61, v16, vcc
	v_add_u32_e32 v16, 0xf800, v64
	v_cndmask_b32_e32 v111, v61, v16, vcc
	v_add_u32_e32 v16, 0xf600, v64
	v_cndmask_b32_e32 v112, v61, v16, vcc
	v_add_u32_e32 v16, 0xf400, v64
	v_cndmask_b32_e32 v113, v61, v16, vcc
	v_add_u32_e32 v16, 0xf200, v64
	v_cndmask_b32_e32 v114, v61, v16, vcc
	v_add_u32_e32 v16, 0xf000, v64
	v_add_u32_e32 v94, v206, v205
	v_cndmask_b32_e32 v115, v61, v16, vcc
	v_add_u32_e32 v16, 0xee00, v64
	v_and_b32_e32 v63, 48, v116
	v_ashrrev_i32_e32 v90, 3, v116
	v_mad_u64_u32 v[52:53], s[18:19], v94, s20, v[116:117]
	v_cndmask_b32_e32 v116, v61, v16, vcc
	v_add_u32_e32 v16, 0xec00, v64
	v_add_u32_e32 v95, v234, v233
	v_cndmask_b32_e32 v122, v61, v16, vcc
	v_add_u32_e32 v16, 0xea00, v64
	v_mad_u64_u32 v[54:55], s[18:19], v95, s20, v[124:125]
	v_add_u32_e32 v96, v237, v236
	v_cndmask_b32_e32 v124, v61, v16, vcc
	v_add_u32_e32 v16, 0xe800, v64
	v_mad_u64_u32 v[56:57], s[18:19], v96, s20, v[126:127]
	v_cndmask_b32_e32 v126, v61, v16, vcc
	v_add_u32_e32 v16, 0xe600, v64
	v_lshl_add_u32 v88, v140, 4, 0
	v_cndmask_b32_e32 v139, v61, v16, vcc
	v_add_u32_e32 v16, 0xe400, v64
	v_mad_i32_i24 v68, v140, -12, v88
	v_cndmask_b32_e32 v140, v61, v16, vcc
	v_add_u32_e32 v16, 0xe200, v64
	v_cndmask_b32_e32 v141, v61, v16, vcc
	v_add_u32_e32 v16, 0xe000, v64
	v_cndmask_b32_e32 v142, v61, v16, vcc
	v_add_u32_e32 v16, 0xde00, v64
	v_cndmask_b32_e32 v143, v61, v16, vcc
	v_add_u32_e32 v16, 0xdc00, v64
	v_cndmask_b32_e32 v144, v61, v16, vcc
	v_add_u32_e32 v16, 0xda00, v64
	v_cndmask_b32_e32 v145, v61, v16, vcc
	v_add_u32_e32 v16, 0xd800, v64
	v_cndmask_b32_e32 v146, v61, v16, vcc
	v_add_u32_e32 v16, 0xd600, v64
	v_cndmask_b32_e32 v147, v61, v16, vcc
	v_and_b32_e32 v16, -16, v52
	v_add_u32_e32 v65, 0xd400, v64
	v_cmp_ne_u32_e64 s[18:19], 16, v16
	v_lshl_add_u32 v16, v94, 6, 0
	v_lshlrev_b32_e32 v53, 5, v52
	s_mov_b32 s28, 0x9c00
	s_movk_i32 s29, 0xc0
	s_movk_i32 s30, 0xff90
	v_cndmask_b32_e32 v148, v61, v65, vcc
	v_add3_u32 v55, v16, v53, s28
	v_mad_u64_u32 v[60:61], s[20:21], v94, s29, v[16:17]
	v_mul_lo_u32 v16, v94, s30
	v_lshlrev_b32_e32 v59, 4, v52
	v_add3_u32 v59, v60, v16, v59
	v_and_b32_e32 v16, -16, v54
	v_cmp_ne_u32_e64 s[20:21], 16, v16
	v_lshl_add_u32 v16, v95, 6, 0
	v_add_u32_e32 v53, v60, v53
	v_lshlrev_b32_e32 v64, 5, v54
	v_mad_u64_u32 v[60:61], s[22:23], v95, s29, v[16:17]
	v_add3_u32 v65, v16, v64, s28
	v_mul_lo_u32 v16, v95, s30
	v_lshlrev_b32_e32 v61, 4, v54
	v_add3_u32 v71, v60, v16, v61
	v_and_b32_e32 v16, -16, v56
	v_cmp_ne_u32_e64 s[22:23], 16, v16
	v_lshl_add_u32 v16, v96, 6, 0
	v_add_u32_e32 v64, v60, v64
	v_lshlrev_b32_e32 v72, 5, v56
	v_mad_u64_u32 v[60:61], s[24:25], v96, s29, v[16:17]
	v_add3_u32 v82, v16, v72, s28
	v_mul_lo_u32 v16, v96, s30
	v_lshlrev_b32_e32 v61, 4, v56
	v_add3_u32 v158, v60, v16, v61
	v_and_b32_e32 v16, -16, v58
	v_cmp_ne_u32_e64 s[24:25], 16, v16
	v_lshl_add_u32 v16, v97, 6, 0
	v_add_u32_e32 v83, v60, v72
	v_lshlrev_b32_e32 v72, 5, v58
	v_mad_u64_u32 v[60:61], s[26:27], v97, s29, v[16:17]
	v_add3_u32 v152, v16, v72, s28
	v_mul_lo_u32 v16, v97, s30
	v_lshlrev_b32_e32 v61, 4, v58
	v_add3_u32 v159, v60, v16, v61
	v_lshl_add_u32 v16, v86, 6, 0
	v_add_u32_e32 v153, v60, v72
	v_lshlrev_b32_e32 v72, 5, v84
	v_mad_u64_u32 v[60:61], s[26:27], v86, s29, v[16:17]
	v_add3_u32 v155, v16, v72, s28
	v_add_u32_e32 v16, v60, v72
	v_mul_lo_u32 v61, v86, s30
	v_lshlrev_b32_e32 v72, 4, v84
	v_mov_b32_e32 v149, s40
	v_mov_b32_e32 v150, s41
	v_cmp_gt_u32_e64 s[26:27], 32, v52
	v_add3_u32 v160, v60, v61, v72
	v_mov_b32_e32 v80, s42
	v_mov_b32_e32 v81, s34
	v_cmp_gt_i32_e32 vcc, 8, v52
	v_cndmask_b32_e64 v61, v149, v150, s[26:27]
	v_mov_b32_e32 v151, s39
	v_cmp_gt_u32_e64 s[26:27], 24, v52
	v_cndmask_b32_e32 v60, v80, v81, vcc
	v_cmp_gt_i32_e64 s[28:29], 16, v52
	v_cndmask_b32_e64 v61, v61, v151, s[26:27]
	v_cmp_gt_u32_e64 s[30:31], 32, v54
	v_cndmask_b32_e64 v60, v61, v60, s[28:29]
	v_lshl_add_u32 v60, v52, 3, v60
	v_ashrrev_i32_e32 v61, 31, v60
	v_lshl_add_u64 v[72:73], v[60:61], 1, s[58:59]
	v_cmp_gt_i32_e64 s[28:29], 8, v54
	v_cndmask_b32_e64 v61, v149, v150, s[30:31]
	v_cmp_gt_u32_e64 s[30:31], 24, v54
	v_cndmask_b32_e64 v60, v80, v81, s[28:29]
	v_cmp_gt_i32_e64 s[34:35], 16, v54
	v_cndmask_b32_e64 v61, v61, v151, s[30:31]
	v_cmp_gt_u32_e64 s[36:37], 32, v56
	v_cndmask_b32_e64 v60, v61, v60, s[34:35]
	v_lshl_add_u32 v60, v54, 3, v60
	v_ashrrev_i32_e32 v61, 31, v60
	v_lshl_add_u64 v[74:75], v[60:61], 1, s[58:59]
	v_cmp_gt_i32_e64 s[34:35], 8, v56
	v_cndmask_b32_e64 v61, v149, v150, s[36:37]
	v_cmp_gt_u32_e64 s[36:37], 24, v56
	v_cndmask_b32_e64 v60, v80, v81, s[34:35]
	v_cmp_gt_i32_e64 s[38:39], 16, v56
	v_cndmask_b32_e64 v61, v61, v151, s[36:37]
	v_cmp_gt_u32_e64 s[40:41], 32, v58
	v_cndmask_b32_e64 v60, v61, v60, s[38:39]
	v_lshl_add_u32 v60, v56, 3, v60
	v_ashrrev_i32_e32 v61, 31, v60
	v_lshl_add_u64 v[76:77], v[60:61], 1, s[58:59]
	v_cmp_gt_i32_e64 s[38:39], 8, v58
	v_cndmask_b32_e64 v61, v149, v150, s[40:41]
	v_cmp_gt_u32_e64 s[40:41], 24, v58
	v_cndmask_b32_e64 v60, v80, v81, s[38:39]
	v_cmp_gt_i32_e64 s[42:43], 16, v58
	v_cndmask_b32_e64 v61, v61, v151, s[40:41]
	v_cmp_gt_u32_e64 s[44:45], 32, v84
	v_cndmask_b32_e64 v60, v61, v60, s[42:43]
	v_lshl_add_u32 v60, v58, 3, v60
	v_ashrrev_i32_e32 v61, 31, v60
	v_lshl_add_u64 v[78:79], v[60:61], 1, s[58:59]
	v_cmp_gt_i32_e64 s[42:43], 8, v84
	v_cndmask_b32_e64 v61, v149, v150, s[44:45]
	v_cmp_gt_u32_e64 s[44:45], 24, v84
	v_cndmask_b32_e64 v60, v80, v81, s[42:43]
	v_cmp_gt_i32_e64 s[48:49], 16, v84
	v_cndmask_b32_e64 v61, v61, v151, s[44:45]
	v_add_u32_e32 v57, 0x1f00, v53
	v_cndmask_b32_e64 v60, v61, v60, s[48:49]
	v_cmp_gt_u32_e64 s[48:49], 16, v52
	v_add_u32_e32 v70, 0x1f00, v64
	v_add_u32_e32 v85, 0x1f00, v83
	v_cndmask_b32_e64 v52, v55, v57, s[48:49]
	v_cndmask_b32_e32 v149, v52, v53, vcc
	v_cmp_gt_u32_e32 vcc, 16, v54
	v_add_u32_e32 v154, 0x1f00, v153
	v_add_u32_e32 v156, 0x1f00, v16
	v_cndmask_b32_e32 v53, v65, v70, vcc
	v_cmp_gt_u32_e32 vcc, 16, v56
	v_lshl_add_u32 v60, v84, 3, v60
	v_mov_b32_e32 v57, 0xc080
	v_cndmask_b32_e32 v54, v82, v85, vcc
	v_cmp_gt_u32_e32 vcc, 16, v58
	v_lshl_add_u32 v66, v90, 9, 0
	v_ashrrev_i32_e32 v61, 31, v60
	v_cndmask_b32_e32 v55, v152, v154, vcc
	v_cmp_gt_u32_e32 vcc, 16, v84
	v_cndmask_b32_e64 v52, v57, v254, s[26:27]
	v_cndmask_b32_e64 v150, v53, v64, s[28:29]
	v_cndmask_b32_e32 v56, v155, v156, vcc
	v_cndmask_b32_e64 v53, v57, v254, s[30:31]
	v_cndmask_b32_e64 v151, v54, v83, s[34:35]
	v_cndmask_b32_e64 v54, v57, v254, s[36:37]
	v_cndmask_b32_e64 v152, v55, v153, s[38:39]
	v_cndmask_b32_e64 v55, v57, v254, s[40:41]
	v_cndmask_b32_e64 v153, v56, v16, s[42:43]
	v_cndmask_b32_e64 v56, v57, v254, s[44:45]
	v_mov_b32_e32 v16, v17
	v_lshl_add_u32 v89, v87, 2, 0
	v_lshl_add_u64 v[80:81], v[60:61], 1, s[58:59]
	s_mov_b32 s34, -8
	v_add_u32_e32 v154, v62, v63
	v_add_u32_e32 v155, v66, v67
	v_add_u32_e32 v156, v59, v52
	v_add_u32_e32 v157, v71, v53
	v_add_u32_e32 v158, v158, v54
	v_add_u32_e32 v159, v159, v55
	v_add_u32_e32 v160, v160, v56
	v_add_u32_e32 v161, v68, v69
	v_mov_b64_e32 v[82:83], v[16:17]
	v_mov_b64_e32 v[84:85], v[16:17]
	v_mov_b32_e32 v52, v232
	v_mov_b32_e32 v53, v231
	v_mov_b32_e32 v54, v230
	v_mov_b32_e32 v55, v207
	s_waitcnt lgkmcnt(0)
	s_barrier
	v_mad_u64_u32 v[218:219], s[26:27], v94, s83, v[72:73]
	v_mad_u64_u32 v[220:221], s[26:27], v95, s83, v[74:75]
	v_mad_u64_u32 v[222:223], s[26:27], v96, s83, v[76:77]
	v_mad_u64_u32 v[244:245], s[26:27], v97, s83, v[78:79]
	v_mad_u64_u32 v[246:247], s[26:27], v86, s83, v[80:81]
	v_and_b32_e32 v98, 31, v119
	v_lshlrev_b32_e32 v98, 3, v98
	v_lshrrev_b32_e32 v99, 5, v119
	s_lshl_b32 s26, s32, 3
	v_add_u32_e32 v99, s26, v99
	v_lshl_add_u32 v99, v99, 2, v228
	v_add_u32_e32 v99, 0x6000, v99
	v_lshrrev_b32_e32 v100, 1, v119
	v_lshlrev_b32_e32 v100, 2, v100
	v_add_u32_e32 v100, 0xd400, v100
	v_lshrrev_b32_e32 v101, 3, v119
	v_lshlrev_b32_e32 v101, 9, v101
	v_and_b32_e32 v102, 7, v119
	v_lshl_add_u32 v101, v102, 6, v101
	v_add_u32_e32 v101, 0xd400, v101
	v_sub_u32_e32 v102, s26, v102
	v_lshlrev_b32_e32 v102, 1, v102
	v_ashrrev_i32_e32 v103, 31, v102
	v_lshl_add_u64 v[102:103], v[18:19], 0, v[102:103]
	s_load_dwordx2 s[26:27], s[84:85], 0x120
	v_lshrrev_b32_e32 v60, 3, v119
	v_and_b32_e32 v61, 7, v119
	v_mov_b32_e32 v62, s82
	v_add_u32_e32 v62, 0xffffff80, v62
	v_bfe_u32 v63, v62, 2, 3
	v_lshlrev_b32_e32 v63, 6, v63
	v_lshrrev_b32_e32 v64, 5, v62
	v_lshlrev_b32_e32 v64, 6, v64
	v_and_b32_e32 v65, 3, v62
	v_lshlrev_b32_e32 v65, 4, v65
	v_lshl_add_u32 v66, v61, 3, v63
	v_lshl_add_u32 v67, v61, 3, v64
	v_add_u32_e32 v67, 0x600, v67
	v_and_b32_e32 v68, 1, v119
	v_lshl_add_u32 v69, v68, 3, v63
	v_add_u32_e32 v69, v69, v65
	v_add_u32_e32 v69, 0x400, v69
	v_mul_u32_u24_e32 v70, 0x1200, v60
	v_lshrrev_b32_e32 v71, 1, v119
	v_mul_u32_u24_e32 v162, 0x1200, v71
	s_waitcnt lgkmcnt(0)
	s_add_u32 s26, s26, 0x6aa8000
	s_addc_u32 s27, s27, 0
	v_lshl_add_u32 v16, v66, 1, v70
	v_lshl_add_u64 v[218:219], v[16:17], 0, s[26:27]
	v_add_u32_e32 v16, 0x400, v16
	v_lshl_add_u64 v[220:221], v[16:17], 0, s[26:27]
	v_and_b32_e32 v62, 15, v119
	v_lshrrev_b32_e32 v63, 6, v119
	v_and_b32_e32 v65, 1, v63
	v_lshl_add_u32 v62, v65, 4, v62
	v_mul_u32_u24_e32 v62, 0x1200, v62
	v_lshrrev_b32_e32 v63, 1, v63
	v_lshlrev_b32_e32 v63, 7, v63
	v_bfe_u32 v65, v119, 4, 2
	v_lshl_add_u32 v63, v65, 3, v63
	v_add_u32_e32 v63, v63, v64
	v_add_u32_e32 v63, 0x600, v63
	v_lshl_add_u32 v16, v63, 1, v62
	v_lshl_add_u64 v[222:223], v[16:17], 0, s[26:27]
	v_add_u32_e32 v16, 64, v16
	v_lshl_add_u64 v[244:245], v[16:17], 0, s[26:27]
	v_lshl_add_u32 v16, v69, 1, v162
	v_lshl_add_u64 v[246:247], v[16:17], 0, s[26:27]
	v_lshlrev_b32_e32 v149, 8, v60
	v_lshl_add_u32 v149, v61, 5, v149
	v_add_u32_e32 v150, 0x2000, v149
	v_mul_u32_u24_e32 v156, 0x90, v60
	v_lshl_add_u32 v156, v61, 4, v156
	v_add_u32_e32 v156, 0xb000, v156
	v_add_u32_e32 v157, 0x1200, v156
	v_lshlrev_b32_e32 v151, 6, v71
	v_lshl_add_u32 v151, v68, 5, v151
	v_add_u32_e32 v151, 0xa000, v151
	v_mul_f32_e32 v117, s73, v117
	v_mul_f32_e32 v121, s73, v121
	v_mul_f32_e32 v123, s73, v123
	v_mul_f32_e32 v125, s73, v125
	v_add_u32_e32 v153, 0x100, v98
	v_add_u32_e32 v159, 0x400, v99
	v_add_u32_e32 v160, 0x800, v98
	v_add_u32_e32 v230, 0x1000, v98
	v_add_u32_e32 v231, 0x1800, v98
	v_add_u32_e32 v152, 0x8000, v161
	v_add_u32_e32 v158, 0x4000, v161
	v_and_b32_e32 v60, 15, v119
	v_mul_u32_u24_e32 v61, 12, v60
	v_add_u32_e32 v91, v91, v61
	v_add_u32_e32 v93, v93, v61
	v_readlane_b32 s26, v255, 18
	s_lshl_b32 s26, s26, 9
	v_mov_b32_e32 v62, s82
	v_add_u32_e32 v62, 0xffffff80, v62
	v_bfe_u32 v62, v62, 2, 3
	v_lshlrev_b32_e32 v62, 6, v62
	v_add_u32_e32 v62, s26, v62
	v_lshl_add_u32 v62, v60, 2, v62
	v_lshlrev_b32_e32 v16, 2, v62
	s_load_dwordx2 s[26:27], s[84:85], 0x78
	s_waitcnt lgkmcnt(0)
	global_load_dword v127, v16, s[26:27]
	global_load_dword v130, v16, s[26:27] offset:4
	global_load_dword v133, v16, s[26:27] offset:8
	global_load_dword v136, v16, s[26:27] offset:12
	s_load_dwordx2 s[26:27], s[84:85], 0x80
	s_waitcnt lgkmcnt(0)
	global_load_dword v128, v16, s[26:27]
	global_load_dword v131, v16, s[26:27] offset:4
	global_load_dword v134, v16, s[26:27] offset:8
	global_load_dword v137, v16, s[26:27] offset:12
	s_load_dwordx2 s[26:27], s[84:85], 0x88
	s_waitcnt lgkmcnt(0)
	global_load_dword v129, v16, s[26:27]
	global_load_dword v132, v16, s[26:27] offset:4
	global_load_dword v135, v16, s[26:27] offset:8
	global_load_dword v138, v16, s[26:27] offset:12
	s_waitcnt vmcnt(0)
	s_branch .LBB0_424

.LBB0_423:
	s_waitcnt lgkmcnt(0)
	s_add_i32 s34, s34, 1
	s_cmpk_eq_i32 s34, 0x200
	v_mov_b64_e32 v[82:83], v[56:57]
	v_mov_b64_e32 v[84:85], v[58:59]
	s_barrier
	s_cbranch_scc1 .LBB0_544
	v_add_u32_e32 v64, 0x8000, v91
	v_add_co_u32_e64 v16, s[26:27], s34, 8
	s_branch .Lrb_c

.Lrb_c:
	v_add_u32_e32 v56, 0x2000, v91
	v_add_u32_e32 v57, 0x8000, v91
	v_add_u32_e32 v58, 0x6000, v91
	v_add_u32_e32 v59, 0x2000, v93
	v_add_u32_e32 v60, 0x8000, v93
	v_add_u32_e32 v61, 0x6000, v93
	ds_read_b128 v[170:173], v57
	ds_read_b128 v[174:177], v56
	ds_read_b128 v[178:181], v91
	ds_read_b128 v[186:189], v60
	ds_read_b128 v[190:193], v59
	ds_read_b128 v[194:197], v93
	v_readfirstlane_b32 s30, v16
	s_and_b64 s[28:29], s[26:27], exec
	s_cselect_b32 s28, s30, s34
	s_cselect_b32 s29, 7, 0x1ff
	s_sub_i32 s29, s29, s28
	s_and_b64 s[26:27], s[26:27], exec
	s_cselect_b32 s31, 0x4000, 0
	s_and_b64 s[26:27], s[64:65], exec
	s_cselect_b32 s26, s28, s29
	s_lshl_b32 s35, s26, 5
	s_add_i32 s35, s35, s31
	s_waitcnt lgkmcnt(3)
	v_add_f32_e32 v206, -1.0, v170
	v_mul_f32_e32 v182, v127, v174
	v_fma_f32 v206, v128, v206, 1.0
	v_mul_f32_e32 v202, v182, v182
	v_mul_f32_e32 v174, v174, v206
	v_mul_f32_e32 v178, v178, v174
	v_mul_f32_e32 v204, v129, v178
	v_add_f32_e32 v206, -1.0, v171
	v_mul_f32_e32 v183, v130, v175
	v_fma_f32 v206, v131, v206, 1.0
	v_fmac_f32_e32 v202, v183, v183
	v_mul_f32_e32 v175, v175, v206
	v_mul_f32_e32 v179, v179, v175
	v_fmac_f32_e32 v204, v132, v179
	v_add_f32_e32 v206, -1.0, v172
	v_mul_f32_e32 v184, v133, v176
	v_fma_f32 v206, v134, v206, 1.0
	v_fmac_f32_e32 v202, v184, v184
	v_mul_f32_e32 v176, v176, v206
	v_mul_f32_e32 v180, v180, v176
	v_fmac_f32_e32 v204, v135, v180
	v_add_f32_e32 v206, -1.0, v173
	v_mul_f32_e32 v185, v136, v177
	v_fma_f32 v206, v137, v206, 1.0
	v_fmac_f32_e32 v202, v185, v185
	v_mul_f32_e32 v177, v177, v206
	v_mul_f32_e32 v181, v181, v177
	v_fmac_f32_e32 v204, v138, v181
	ds_write_b128 v56, v[174:177]
	s_waitcnt lgkmcnt(1)
	v_add_f32_e32 v207, -1.0, v186
	v_mul_f32_e32 v198, v127, v190
	v_fma_f32 v207, v128, v207, 1.0
	v_mul_f32_e32 v203, v198, v198
	v_mul_f32_e32 v190, v190, v207
	v_mul_f32_e32 v194, v194, v190
	v_mul_f32_e32 v205, v129, v194
	v_add_f32_e32 v207, -1.0, v187
	v_mul_f32_e32 v199, v130, v191
	v_fma_f32 v207, v131, v207, 1.0
	v_fmac_f32_e32 v203, v199, v199
	v_mul_f32_e32 v191, v191, v207
	v_mul_f32_e32 v195, v195, v191
	v_fmac_f32_e32 v205, v132, v195
	v_add_f32_e32 v207, -1.0, v188
	v_mul_f32_e32 v200, v133, v192
	v_fma_f32 v207, v134, v207, 1.0
	v_fmac_f32_e32 v203, v200, v200
	v_mul_f32_e32 v192, v192, v207
	v_mul_f32_e32 v196, v196, v192
	v_fmac_f32_e32 v205, v135, v196
	v_add_f32_e32 v207, -1.0, v189
	v_mul_f32_e32 v201, v136, v193
	v_fma_f32 v207, v137, v207, 1.0
	v_fmac_f32_e32 v203, v201, v201
	v_mul_f32_e32 v193, v193, v207
	v_mul_f32_e32 v197, v197, v193
	v_fmac_f32_e32 v205, v138, v197
	ds_write_b128 v59, v[190:193]
	s_nop 1
	v_add_f32_dpp v202, v202, v202 quad_perm:[1,0,3,2] row_mask:0xf bank_mask:0xf bound_ctrl:1
	v_add_f32_dpp v203, v203, v203 quad_perm:[1,0,3,2] row_mask:0xf bank_mask:0xf bound_ctrl:1
	v_add_f32_dpp v204, v204, v204 quad_perm:[1,0,3,2] row_mask:0xf bank_mask:0xf bound_ctrl:1
	v_add_f32_dpp v205, v205, v205 quad_perm:[1,0,3,2] row_mask:0xf bank_mask:0xf bound_ctrl:1
	v_add_f32_dpp v202, v202, v202 quad_perm:[2,3,0,1] row_mask:0xf bank_mask:0xf bound_ctrl:1
	v_add_f32_dpp v203, v203, v203 quad_perm:[2,3,0,1] row_mask:0xf bank_mask:0xf bound_ctrl:1
	v_add_f32_dpp v204, v204, v204 quad_perm:[2,3,0,1] row_mask:0xf bank_mask:0xf bound_ctrl:1
	v_add_f32_dpp v205, v205, v205 quad_perm:[2,3,0,1] row_mask:0xf bank_mask:0xf bound_ctrl:1
	v_add_f32_dpp v202, v202, v202 row_half_mirror row_mask:0xf bank_mask:0xf bound_ctrl:1
	v_add_f32_dpp v203, v203, v203 row_half_mirror row_mask:0xf bank_mask:0xf bound_ctrl:1
	v_add_f32_dpp v204, v204, v204 row_half_mirror row_mask:0xf bank_mask:0xf bound_ctrl:1
	v_add_f32_dpp v205, v205, v205 row_half_mirror row_mask:0xf bank_mask:0xf bound_ctrl:1
	v_add_f32_dpp v202, v202, v202 row_mirror row_mask:0xf bank_mask:0xf bound_ctrl:1
	v_add_f32_dpp v203, v203, v203 row_mirror row_mask:0xf bank_mask:0xf bound_ctrl:1
	v_add_f32_dpp v204, v204, v204 row_mirror row_mask:0xf bank_mask:0xf bound_ctrl:1
	v_add_f32_dpp v205, v205, v205 row_mirror row_mask:0xf bank_mask:0xf bound_ctrl:1
	v_sqrt_f32_e32 v202, v202
	v_sqrt_f32_e32 v203, v203
	s_nop 0
	v_max_f32_e32 v202, 0x2b8cbccc, v202
	v_max_f32_e32 v203, 0x2b8cbccc, v203
	v_rcp_f32_e32 v202, v202
	v_rcp_f32_e32 v203, v203
	s_nop 0
	v_mul_f32_e32 v182, v182, v202
	v_mul_f32_e32 v183, v183, v202
	v_mul_f32_e32 v184, v184, v202
	v_mul_f32_e32 v185, v185, v202
	v_mul_f32_e32 v170, v170, v182
	v_mul_f32_e32 v171, v171, v183
	v_mul_f32_e32 v172, v172, v184
	v_mul_f32_e32 v173, v173, v185
	ds_write_b128 v58, v[182:185]
	ds_write_b128 v57, v[170:173]
	v_mul_f32_e32 v198, v198, v203
	v_mul_f32_e32 v199, v199, v203
	v_mul_f32_e32 v200, v200, v203
	v_mul_f32_e32 v201, v201, v203
	v_mul_f32_e32 v186, v186, v198
	v_mul_f32_e32 v187, v187, v199
	v_mul_f32_e32 v188, v188, v200
	v_mul_f32_e32 v189, v189, v201
	ds_write_b128 v61, v[198:201]
	ds_write_b128 v60, v[186:189]
	s_and_saveexec_b64 s[26:27], s[16:17]
	s_cbranch_execz .LBB0_492
	v_add_u32_e32 v62, s35, v87
	v_ashrrev_i32_e32 v63, 31, v62
	v_lshlrev_b64 v[62:63], 5, v[62:63]
	v_lshl_add_u64 v[62:63], s[78:79], 0, v[62:63]
	global_store_dword v[62:63], v204, off
	v_add_u32_e32 v62, s35, v92
	v_ashrrev_i32_e32 v63, 31, v62
	v_lshlrev_b64 v[62:63], 5, v[62:63]
	v_lshl_add_u64 v[62:63], s[78:79], 0, v[62:63]
	global_store_dword v[62:63], v205, off

.Lrs_post:
	v_mov_b64_e32 v[56:57], v[82:83]
	s_waitcnt lgkmcnt(0)
	s_barrier
	ds_read_b128 v[60:63], v101
	ds_read_b128 v[64:67], v101 offset:16
	ds_read_b128 v[68:71], v101 offset:32
	ds_read_b128 v[162:165], v101 offset:48
	v_add_u32_e32 v170, s35, v90
	v_ashrrev_i32_e32 v171, 31, v170
	v_lshlrev_b64 v[170:171], 10, v[170:171]
	v_lshl_add_u64 v[170:171], v[102:103], 0, v[170:171]
	s_waitcnt lgkmcnt(2)
	v_add_f32_e32 v60, v60, v61
	v_add_f32_e32 v62, v62, v63
	v_add_f32_e32 v64, v64, v65
	v_add_f32_e32 v66, v66, v67
	v_add_f32_e32 v60, v60, v62
	v_add_f32_e32 v64, v64, v66
	s_waitcnt lgkmcnt(0)
	v_add_f32_e32 v68, v68, v69
	v_add_f32_e32 v70, v70, v71
	v_add_f32_e32 v162, v162, v163
	v_add_f32_e32 v164, v164, v165
	v_add_f32_e32 v68, v68, v70
	v_add_f32_e32 v162, v162, v164
	v_add_f32_e32 v60, v60, v64
	v_add_f32_e32 v68, v68, v162
	v_add_f32_e32 v60, v60, v68
	s_nop 1
	v_mov_b32_dpp v61, v60 quad_perm:[1,0,3,2] row_mask:0xf bank_mask:0xf bound_ctrl:1
	s_nop 0
	v_cvt_pk_bf16_f32 v16, v60, v61
	s_mov_b32 s26, 0x55555555
	s_mov_b32 s27, 0x55555555
	s_and_b64 exec, exec, s[26:27]
	global_atomic_pk_add_bf16 v[170:171], v16, off
	s_mov_b64 exec, -1
	s_andn2_b64 vcc, exec, s[28:29]
	s_cbranch_vccnz .LBB0_423
	s_waitcnt vmcnt(1)
	v_lshlrev_b32_e32 v60, 16, v20
	v_and_b32_e32 v61, 0xffff0000, v20
	v_lshlrev_b32_e32 v62, 16, v21
	v_and_b32_e32 v63, 0xffff0000, v21
	v_lshlrev_b32_e32 v64, 16, v22
	v_and_b32_e32 v65, 0xffff0000, v22
	v_lshlrev_b32_e32 v66, 16, v23
	v_and_b32_e32 v67, 0xffff0000, v23
	ds_write_b128 v149, v[60:63]
	ds_write_b128 v149, v[64:67] offset:16
	v_lshlrev_b32_e32 v162, 16, v52
	v_and_b32_e32 v163, 0xffff0000, v52
	v_lshlrev_b32_e32 v164, 16, v53
	v_and_b32_e32 v165, 0xffff0000, v53
	v_lshlrev_b32_e32 v166, 16, v54
	v_and_b32_e32 v167, 0xffff0000, v54
	v_lshlrev_b32_e32 v168, 16, v55
	v_and_b32_e32 v169, 0xffff0000, v55
	ds_write_b128 v150, v[162:165]
	ds_write_b128 v150, v[166:169] offset:16
	s_and_saveexec_b64 s[26:27], s[14:15]
	s_cbranch_execz .Lrc_skip
	v_lshlrev_b32_e32 v60, 16, v48
	v_and_b32_e32 v61, 0xffff0000, v48
	v_lshlrev_b32_e32 v62, 16, v49
	v_and_b32_e32 v63, 0xffff0000, v49
	v_lshlrev_b32_e32 v64, 16, v50
	v_and_b32_e32 v65, 0xffff0000, v50
	v_lshlrev_b32_e32 v66, 16, v51
	v_and_b32_e32 v67, 0xffff0000, v51
	ds_write_b128 v151, v[60:63]
	ds_write_b128 v151, v[64:67] offset:16
.Lrc_skip:
	s_or_b64 exec, exec, s[26:27]
	v_mfma_f32_16x16x32_bf16 v[68:71], v[28:31], v[4:7], 0
	v_mfma_f32_16x16x32_bf16 v[64:67], v[28:31], v[8:11], 0
	v_mfma_f32_16x16x32_bf16 v[60:63], v[28:31], v[12:15], 0
	v_mfma_f32_16x16x32_bf16 v[166:169], v[28:31], v[24:27], 0
	v_mfma_f32_16x16x32_bf16 v[68:71], v[0:3], v[32:35], v[68:71]
	v_mfma_f32_16x16x32_bf16 v[64:67], v[0:3], v[36:39], v[64:67]
	v_mfma_f32_16x16x32_bf16 v[60:63], v[0:3], v[40:43], v[60:63]
	v_mfma_f32_16x16x32_bf16 v[166:169], v[0:3], v[44:47], v[166:169]
	s_nop 7
	v_fma_f32 v170, v68, s73, v117
	v_fma_f32 v171, v69, s73, v117
	v_fma_f32 v172, v70, s73, v117
	v_fma_f32 v173, v71, s73, v117
	v_fma_f32 v174, v64, s73, v121
	v_fma_f32 v175, v65, s73, v121
	v_fma_f32 v176, v66, s73, v121
	v_fma_f32 v177, v67, s73, v121
	v_fma_f32 v178, v60, s73, v123
	v_fma_f32 v179, v61, s73, v123
	v_fma_f32 v180, v62, s73, v123
	v_fma_f32 v181, v63, s73, v123
	v_fma_f32 v182, v166, s73, v125
	v_fma_f32 v183, v167, s73, v125
	v_fma_f32 v184, v168, s73, v125
	v_fma_f32 v185, v169, s73, v125
	v_exp_f32_e32 v170, v170
	v_exp_f32_e32 v171, v171
	v_exp_f32_e32 v172, v172
	v_exp_f32_e32 v173, v173
	v_exp_f32_e32 v174, v174
	v_exp_f32_e32 v175, v175
	v_exp_f32_e32 v176, v176
	v_exp_f32_e32 v177, v177
	v_exp_f32_e32 v178, v178
	v_exp_f32_e32 v179, v179
	v_exp_f32_e32 v180, v180
	v_exp_f32_e32 v181, v181
	v_exp_f32_e32 v182, v182
	v_exp_f32_e32 v183, v183
	v_exp_f32_e32 v184, v184
	v_exp_f32_e32 v185, v185
	v_add_f32_e32 v170, 1.0, v170
	v_add_f32_e32 v171, 1.0, v171
	v_add_f32_e32 v172, 1.0, v172
	v_add_f32_e32 v173, 1.0, v173
	v_add_f32_e32 v174, 1.0, v174
	v_add_f32_e32 v175, 1.0, v175
	v_add_f32_e32 v176, 1.0, v176
	v_add_f32_e32 v177, 1.0, v177
	v_add_f32_e32 v178, 1.0, v178
	v_add_f32_e32 v179, 1.0, v179
	v_add_f32_e32 v180, 1.0, v180
	v_add_f32_e32 v181, 1.0, v181
	v_add_f32_e32 v182, 1.0, v182
	v_add_f32_e32 v183, 1.0, v183
	v_add_f32_e32 v184, 1.0, v184
	v_add_f32_e32 v185, 1.0, v185
	v_rcp_f32_e32 v170, v170
	v_rcp_f32_e32 v171, v171
	v_rcp_f32_e32 v172, v172
	v_rcp_f32_e32 v173, v173
	v_rcp_f32_e32 v174, v174
	v_rcp_f32_e32 v175, v175
	v_rcp_f32_e32 v176, v176
	v_rcp_f32_e32 v177, v177
	v_rcp_f32_e32 v178, v178
	v_rcp_f32_e32 v179, v179
	v_rcp_f32_e32 v180, v180
	v_rcp_f32_e32 v181, v181
	v_rcp_f32_e32 v182, v182
	v_rcp_f32_e32 v183, v183
	v_rcp_f32_e32 v184, v184
	v_rcp_f32_e32 v185, v185
	s_and_b64 vcc, exec, s[4:5]
	s_cbranch_vccz .Lrb2_p0
	ds_write2_b32 v152, v170, v171 offset0:0 offset1:64
	ds_write2_b32 v152, v172, v173 offset0:128 offset1:192
	ds_write2_b32 v152, v174, v175 offset0:16 offset1:80
	ds_write2_b32 v152, v176, v177 offset0:144 offset1:208
	ds_write2_b32 v152, v178, v179 offset0:32 offset1:96
	ds_write2_b32 v152, v180, v181 offset0:160 offset1:224
	ds_write2_b32 v152, v182, v183 offset0:48 offset1:112
	ds_write2_b32 v152, v184, v185 offset0:176 offset1:240
	s_branch .Lrb2_done
.Lrb2_p0:
	v_mul_f32_e32 v170, 0xbf1b4598, v170
	v_mul_f32_e32 v171, 0xbf1b4598, v171
	v_mul_f32_e32 v172, 0xbf1b4598, v172
	v_mul_f32_e32 v173, 0xbf1b4598, v173
	v_mul_f32_e32 v174, 0xbf1b4598, v174
	v_mul_f32_e32 v175, 0xbf1b4598, v175
	v_mul_f32_e32 v176, 0xbf1b4598, v176
	v_mul_f32_e32 v177, 0xbf1b4598, v177
	v_mul_f32_e32 v178, 0xbf1b4598, v178
	v_mul_f32_e32 v179, 0xbf1b4598, v179
	v_mul_f32_e32 v180, 0xbf1b4598, v180
	v_mul_f32_e32 v181, 0xbf1b4598, v181
	v_mul_f32_e32 v182, 0xbf1b4598, v182
	v_mul_f32_e32 v183, 0xbf1b4598, v183
	v_mul_f32_e32 v184, 0xbf1b4598, v184
	v_mul_f32_e32 v185, 0xbf1b4598, v185
	v_mul_f32_e32 v170, 0x3fb8aa3b, v170
	v_mul_f32_e32 v171, 0x3fb8aa3b, v171
	v_mul_f32_e32 v172, 0x3fb8aa3b, v172
	v_mul_f32_e32 v173, 0x3fb8aa3b, v173
	v_mul_f32_e32 v174, 0x3fb8aa3b, v174
	v_mul_f32_e32 v175, 0x3fb8aa3b, v175
	v_mul_f32_e32 v176, 0x3fb8aa3b, v176
	v_mul_f32_e32 v177, 0x3fb8aa3b, v177
	v_mul_f32_e32 v178, 0x3fb8aa3b, v178
	v_mul_f32_e32 v179, 0x3fb8aa3b, v179
	v_mul_f32_e32 v180, 0x3fb8aa3b, v180
	v_mul_f32_e32 v181, 0x3fb8aa3b, v181
	v_mul_f32_e32 v182, 0x3fb8aa3b, v182
	v_mul_f32_e32 v183, 0x3fb8aa3b, v183
	v_mul_f32_e32 v184, 0x3fb8aa3b, v184
	v_mul_f32_e32 v185, 0x3fb8aa3b, v185
	v_exp_f32_e32 v170, v170
	v_exp_f32_e32 v171, v171
	v_exp_f32_e32 v172, v172
	v_exp_f32_e32 v173, v173
	v_exp_f32_e32 v174, v174
	v_exp_f32_e32 v175, v175
	v_exp_f32_e32 v176, v176
	v_exp_f32_e32 v177, v177
	v_exp_f32_e32 v178, v178
	v_exp_f32_e32 v179, v179
	v_exp_f32_e32 v180, v180
	v_exp_f32_e32 v181, v181
	v_exp_f32_e32 v182, v182
	v_exp_f32_e32 v183, v183
	v_exp_f32_e32 v184, v184
	v_exp_f32_e32 v185, v185
	ds_write2_b32 v158, v170, v171 offset0:0 offset1:64
	ds_write2_b32 v158, v172, v173 offset0:128 offset1:192
	ds_write2_b32 v158, v174, v175 offset0:16 offset1:80
	ds_write2_b32 v158, v176, v177 offset0:144 offset1:208
	ds_write2_b32 v158, v178, v179 offset0:32 offset1:96
	ds_write2_b32 v158, v180, v181 offset0:160 offset1:224
	ds_write2_b32 v158, v182, v183 offset0:48 offset1:112
	ds_write2_b32 v158, v184, v185 offset0:176 offset1:240
.Lrb2_done:
	s_branch .LBB0_423
.LBB0_544:
	s_mov_b64 s[4:5], 0
